# LRU pass 2: 16 gate gelu values evaluated together with the recurrence interleaved
# baseline (speedup 1.0000x reference)
; #define LAS __attribute__((address_space(3)))
; __device__ __forceinline__ float bf2f(bf16_t b) { return __uint_as_float((unsigned)b << 16); }
; __device__ __forceinline__ float gelu_tanh(float x) { const float y = 0.7978845608028654f * (x + 0.044715f * x * x * x); const float e = __expf(2.f * y); return 0.5f * x * (2.f - 2.f * __builtin_amdgcn_rcpf(1.f + e)); }
; __device__ __forceinline__ void lru_chain(unsigned char* ws_, const float* const* in_, int l_, LAS unsigned char* lds, int tid, int bid, int G) {
;     ...
;             float hin = CAR[(chunk & 1) * 64 + lane];
;             for (int sgi = 0; sgi < w; ++sgi) hin = SA[sgi * 64 + lane] * hin + SB[sgi * 64 + lane];
;             hh = hin;
; #pragma unroll
;             for (int i = 0; i < 16; i += 2) { hh = av[i] * hh + bv[i]; const float h0 = hh; hh = av[i + 1] * hh + bv[i + 1]; const int tl = 16 * w + i;
;                 const float g0 = gelu_tanh(bf2f(*(const LAS bf16_t*)(GT + tl * 144 + lane * 2))), g1 = gelu_tanh(bf2f(*(const LAS bf16_t*)(GT + (tl + 1) * 144 + lane * 2)));
.LBB0_203:
	s_waitcnt lgkmcnt(0)
	ds_read_u16 v216, v204
	ds_read_u16 v217, v204 offset:144
	ds_read_u16 v218, v204 offset:288
	ds_read_u16 v219, v204 offset:432
	ds_read_u16 v220, v204 offset:576
	ds_read_u16 v221, v204 offset:720
	ds_read_u16 v222, v204 offset:864
	ds_read_u16 v223, v204 offset:1008
	ds_read_u16 v224, v204 offset:1152
	ds_read_u16 v225, v204 offset:1296
	ds_read_u16 v226, v204 offset:1440
	ds_read_u16 v227, v204 offset:1584
	ds_read_u16 v228, v204 offset:1728
	ds_read_u16 v229, v204 offset:1872
	ds_read_u16 v230, v204 offset:2016
	ds_read_u16 v231, v204 offset:2160
	s_and_b64 vcc, exec, s[50:51]
	s_waitcnt lgkmcnt(15)
	v_lshlrev_b32_e32 v216, 16, v216
	s_waitcnt lgkmcnt(14)
	v_lshlrev_b32_e32 v217, 16, v217
	s_waitcnt lgkmcnt(13)
	v_lshlrev_b32_e32 v218, 16, v218
	s_waitcnt lgkmcnt(12)
	v_lshlrev_b32_e32 v219, 16, v219
	s_waitcnt lgkmcnt(11)
	v_lshlrev_b32_e32 v220, 16, v220
	s_waitcnt lgkmcnt(10)
	v_lshlrev_b32_e32 v221, 16, v221
	s_waitcnt lgkmcnt(9)
	v_lshlrev_b32_e32 v222, 16, v222
	s_waitcnt lgkmcnt(8)
	v_lshlrev_b32_e32 v223, 16, v223
	s_waitcnt lgkmcnt(7)
	v_lshlrev_b32_e32 v224, 16, v224
	s_waitcnt lgkmcnt(6)
	v_lshlrev_b32_e32 v225, 16, v225
	s_waitcnt lgkmcnt(5)
	v_lshlrev_b32_e32 v226, 16, v226
	s_waitcnt lgkmcnt(4)
	v_lshlrev_b32_e32 v227, 16, v227
	s_waitcnt lgkmcnt(3)
	v_lshlrev_b32_e32 v228, 16, v228
	s_waitcnt lgkmcnt(2)
	v_lshlrev_b32_e32 v229, 16, v229
	s_waitcnt lgkmcnt(1)
	v_lshlrev_b32_e32 v230, 16, v230
	s_waitcnt lgkmcnt(0)
	v_lshlrev_b32_e32 v231, 16, v231
	v_fma_f32 v96, v100, v1, v96
	v_fmac_f32_e32 v97, v101, v96
	v_mul_f32_e32 v179, 0x3d372713, v216
	v_mul_f32_e32 v180, 0x3d372713, v217
	v_mul_f32_e32 v181, 0x3d372713, v218
	v_mul_f32_e32 v182, 0x3d372713, v219
	v_mul_f32_e32 v183, 0x3d372713, v220
	v_mul_f32_e32 v184, 0x3d372713, v221
	v_mul_f32_e32 v185, 0x3d372713, v222
	v_mul_f32_e32 v186, 0x3d372713, v223
	v_mul_f32_e32 v234, 0x3d372713, v224
	v_mul_f32_e32 v236, 0x3d372713, v225
	v_mul_f32_e32 v238, 0x3d372713, v226
	v_mul_f32_e32 v240, 0x3d372713, v227
	v_mul_f32_e32 v242, 0x3d372713, v228
	v_mul_f32_e32 v244, 0x3d372713, v229
	v_mul_f32_e32 v246, 0x3d372713, v230
	v_mul_f32_e32 v248, 0x3d372713, v231
	v_fmac_f32_e32 v92, v98, v97
	v_fmac_f32_e32 v93, v99, v92
	v_mul_f32_e32 v179, v179, v216
	v_mul_f32_e32 v180, v180, v217
	v_mul_f32_e32 v181, v181, v218
	v_mul_f32_e32 v182, v182, v219
	v_mul_f32_e32 v183, v183, v220
	v_mul_f32_e32 v184, v184, v221
	v_mul_f32_e32 v185, v185, v222
	v_mul_f32_e32 v186, v186, v223
	v_mul_f32_e32 v234, v234, v224
	v_mul_f32_e32 v236, v236, v225
	v_mul_f32_e32 v238, v238, v226
	v_mul_f32_e32 v240, v240, v227
	v_mul_f32_e32 v242, v242, v228
	v_mul_f32_e32 v244, v244, v229
	v_mul_f32_e32 v246, v246, v230
	v_mul_f32_e32 v248, v248, v231
	v_fmac_f32_e32 v88, v94, v93
	v_fmac_f32_e32 v89, v95, v88
	v_fma_f32 v179, v179, v216, v216
	v_fma_f32 v180, v180, v217, v217
	v_fma_f32 v181, v181, v218, v218
	v_fma_f32 v182, v182, v219, v219
	v_fma_f32 v183, v183, v220, v220
	v_fma_f32 v184, v184, v221, v221
	v_fma_f32 v185, v185, v222, v222
	v_fma_f32 v186, v186, v223, v223
	v_fma_f32 v234, v234, v224, v224
	v_fma_f32 v236, v236, v225, v225
	v_fma_f32 v238, v238, v226, v226
	v_fma_f32 v240, v240, v227, v227
	v_fma_f32 v242, v242, v228, v228
	v_fma_f32 v244, v244, v229, v229
	v_fma_f32 v246, v246, v230, v230
	v_fma_f32 v248, v248, v231, v231
	v_fmac_f32_e32 v84, v90, v89
	v_fmac_f32_e32 v85, v91, v84
	v_mul_f32_e32 v179, 0x3f4c422a, v179
	v_mul_f32_e32 v180, 0x3f4c422a, v180
	v_mul_f32_e32 v181, 0x3f4c422a, v181
	v_mul_f32_e32 v182, 0x3f4c422a, v182
	v_mul_f32_e32 v183, 0x3f4c422a, v183
	v_mul_f32_e32 v184, 0x3f4c422a, v184
	v_mul_f32_e32 v185, 0x3f4c422a, v185
	v_mul_f32_e32 v186, 0x3f4c422a, v186
	v_mul_f32_e32 v234, 0x3f4c422a, v234
	v_mul_f32_e32 v236, 0x3f4c422a, v236
	v_mul_f32_e32 v238, 0x3f4c422a, v238
	v_mul_f32_e32 v240, 0x3f4c422a, v240
	v_mul_f32_e32 v242, 0x3f4c422a, v242
	v_mul_f32_e32 v244, 0x3f4c422a, v244
	v_mul_f32_e32 v246, 0x3f4c422a, v246
	v_mul_f32_e32 v248, 0x3f4c422a, v248
	v_fmac_f32_e32 v80, v86, v85
	v_fmac_f32_e32 v81, v87, v80
	v_add_f32_e32 v179, v179, v179
	v_add_f32_e32 v180, v180, v180
	v_add_f32_e32 v181, v181, v181
	v_add_f32_e32 v182, v182, v182
	v_add_f32_e32 v183, v183, v183
	v_add_f32_e32 v184, v184, v184
	v_add_f32_e32 v185, v185, v185
	v_add_f32_e32 v186, v186, v186
	v_add_f32_e32 v234, v234, v234
	v_add_f32_e32 v236, v236, v236
	v_add_f32_e32 v238, v238, v238
	v_add_f32_e32 v240, v240, v240
	v_add_f32_e32 v242, v242, v242
	v_add_f32_e32 v244, v244, v244
	v_add_f32_e32 v246, v246, v246
	v_add_f32_e32 v248, v248, v248
	v_fmac_f32_e32 v76, v82, v81
	v_fmac_f32_e32 v77, v83, v76
	v_mul_f32_e32 v179, 0x3fb8aa3b, v179
	v_mul_f32_e32 v180, 0x3fb8aa3b, v180
	v_mul_f32_e32 v181, 0x3fb8aa3b, v181
	v_mul_f32_e32 v182, 0x3fb8aa3b, v182
	v_mul_f32_e32 v183, 0x3fb8aa3b, v183
	v_mul_f32_e32 v184, 0x3fb8aa3b, v184
	v_mul_f32_e32 v185, 0x3fb8aa3b, v185
; #define LAS __attribute__((address_space(3)))
; __device__ __forceinline__ float bf2f(bf16_t b) { return __uint_as_float((unsigned)b << 16); }
; __device__ __forceinline__ unsigned cvt_pk_bf16(float lo, float hi) { unsigned r; asm volatile("v_cvt_pk_bf16_f32 %0, %1, %2" : "=v"(r) : "v"(lo), "v"(hi)); return r; }
; __device__ __forceinline__ float gelu_tanh(float x) { const float y = 0.7978845608028654f * (x + 0.044715f * x * x * x); const float e = __expf(2.f * y); return 0.5f * x * (2.f - 2.f * __builtin_amdgcn_rcpf(1.f + e)); }
; __device__ __forceinline__ void lru_chain(unsigned char* ws_, const float* const* in_, int l_, LAS unsigned char* lds, int tid, int bid, int G) {
;     ...
;             for (int i = 0; i < 16; i += 2) { hh = av[i] * hh + bv[i]; const float h0 = hh; hh = av[i + 1] * hh + bv[i + 1]; const int tl = 16 * w + i;
;                 const float g0 = gelu_tanh(bf2f(*(const LAS bf16_t*)(GT + tl * 144 + lane * 2))), g1 = gelu_tanh(bf2f(*(const LAS bf16_t*)(GT + (tl + 1) * 144 + lane * 2)));
;                 const unsigned pk = cvt_pk_bf16(g0 * h0, g1 * hh);
;                 *(LAS bf16_t*)(OT + tl * 144 + lane * 2) = (bf16_t)(pk & 0xffffu); *(LAS bf16_t*)(OT + (tl + 1) * 144 + lane * 2) = (bf16_t)(pk >> 16); }
;             if (w == 7) CAR[((chunk + 1) & 1) * 64 + lane] = hh;
	v_mul_f32_e32 v186, 0x3fb8aa3b, v186
	v_mul_f32_e32 v234, 0x3fb8aa3b, v234
	v_mul_f32_e32 v236, 0x3fb8aa3b, v236
	v_mul_f32_e32 v238, 0x3fb8aa3b, v238
	v_mul_f32_e32 v240, 0x3fb8aa3b, v240
	v_mul_f32_e32 v242, 0x3fb8aa3b, v242
	v_mul_f32_e32 v244, 0x3fb8aa3b, v244
	v_mul_f32_e32 v246, 0x3fb8aa3b, v246
	v_mul_f32_e32 v248, 0x3fb8aa3b, v248
	v_fmac_f32_e32 v72, v78, v77
	v_fmac_f32_e32 v73, v79, v72
	v_exp_f32_e32 v179, v179
	v_exp_f32_e32 v180, v180
	v_exp_f32_e32 v181, v181
	v_exp_f32_e32 v182, v182
	v_exp_f32_e32 v183, v183
	v_exp_f32_e32 v184, v184
	v_exp_f32_e32 v185, v185
	v_exp_f32_e32 v186, v186
	v_exp_f32_e32 v234, v234
	v_exp_f32_e32 v236, v236
	v_exp_f32_e32 v238, v238
	v_exp_f32_e32 v240, v240
	v_exp_f32_e32 v242, v242
	v_exp_f32_e32 v244, v244
	v_exp_f32_e32 v246, v246
	v_exp_f32_e32 v248, v248
	v_fmac_f32_e32 v2, v74, v73
	v_fmac_f32_e32 v3, v75, v2
	v_mul_f32_e32 v216, 0.5, v216
	v_mul_f32_e32 v217, 0.5, v217
	v_mul_f32_e32 v218, 0.5, v218
	v_mul_f32_e32 v219, 0.5, v219
	v_mul_f32_e32 v220, 0.5, v220
	v_mul_f32_e32 v221, 0.5, v221
	v_mul_f32_e32 v222, 0.5, v222
	v_mul_f32_e32 v223, 0.5, v223
	v_mul_f32_e32 v224, 0.5, v224
	v_mul_f32_e32 v225, 0.5, v225
	v_mul_f32_e32 v226, 0.5, v226
	v_mul_f32_e32 v227, 0.5, v227
	v_mul_f32_e32 v228, 0.5, v228
	v_mul_f32_e32 v229, 0.5, v229
	v_mul_f32_e32 v230, 0.5, v230
	v_mul_f32_e32 v231, 0.5, v231
	v_add_f32_e32 v179, 1.0, v179
	v_add_f32_e32 v180, 1.0, v180
	v_add_f32_e32 v181, 1.0, v181
	v_add_f32_e32 v182, 1.0, v182
	v_add_f32_e32 v183, 1.0, v183
	v_add_f32_e32 v184, 1.0, v184
	v_add_f32_e32 v185, 1.0, v185
	v_add_f32_e32 v186, 1.0, v186
	v_add_f32_e32 v234, 1.0, v234
	v_add_f32_e32 v236, 1.0, v236
	v_add_f32_e32 v238, 1.0, v238
	v_add_f32_e32 v240, 1.0, v240
	v_add_f32_e32 v242, 1.0, v242
	v_add_f32_e32 v244, 1.0, v244
	v_add_f32_e32 v246, 1.0, v246
	v_add_f32_e32 v248, 1.0, v248
	v_rcp_f32_e32 v179, v179
	v_rcp_f32_e32 v180, v180
	v_rcp_f32_e32 v181, v181
	v_rcp_f32_e32 v182, v182
	v_rcp_f32_e32 v183, v183
	v_rcp_f32_e32 v184, v184
	v_rcp_f32_e32 v185, v185
	v_rcp_f32_e32 v186, v186
	v_rcp_f32_e32 v234, v234
	v_rcp_f32_e32 v236, v236
	v_rcp_f32_e32 v238, v238
	v_rcp_f32_e32 v240, v240
	v_rcp_f32_e32 v242, v242
	v_rcp_f32_e32 v244, v244
	v_rcp_f32_e32 v246, v246
	v_rcp_f32_e32 v248, v248
	v_fma_f32 v179, v179, -2.0, 2.0
	v_fma_f32 v180, v180, -2.0, 2.0
	v_fma_f32 v181, v181, -2.0, 2.0
	v_fma_f32 v182, v182, -2.0, 2.0
	v_fma_f32 v183, v183, -2.0, 2.0
	v_fma_f32 v184, v184, -2.0, 2.0
	v_fma_f32 v185, v185, -2.0, 2.0
	v_fma_f32 v186, v186, -2.0, 2.0
	v_fma_f32 v234, v234, -2.0, 2.0
	v_fma_f32 v236, v236, -2.0, 2.0
	v_fma_f32 v238, v238, -2.0, 2.0
	v_fma_f32 v240, v240, -2.0, 2.0
	v_fma_f32 v242, v242, -2.0, 2.0
	v_fma_f32 v244, v244, -2.0, 2.0
	v_fma_f32 v246, v246, -2.0, 2.0
	v_fma_f32 v248, v248, -2.0, 2.0
	v_mul_f32_e32 v216, v216, v179
	v_mul_f32_e32 v217, v217, v180
	v_mul_f32_e32 v218, v218, v181
	v_mul_f32_e32 v219, v219, v182
	v_mul_f32_e32 v220, v220, v183
	v_mul_f32_e32 v221, v221, v184
	v_mul_f32_e32 v222, v222, v185
	v_mul_f32_e32 v223, v223, v186
	v_mul_f32_e32 v224, v224, v234
	v_mul_f32_e32 v225, v225, v236
	v_mul_f32_e32 v226, v226, v238
	v_mul_f32_e32 v227, v227, v240
	v_mul_f32_e32 v228, v228, v242
	v_mul_f32_e32 v229, v229, v244
	v_mul_f32_e32 v230, v230, v246
	v_mul_f32_e32 v231, v231, v248
	v_mul_f32_e32 v179, v96, v216
	v_mul_f32_e32 v180, v97, v217
	v_mul_f32_e32 v181, v92, v218
	v_mul_f32_e32 v182, v93, v219
	v_mul_f32_e32 v183, v88, v220
	v_mul_f32_e32 v184, v89, v221
	v_mul_f32_e32 v185, v84, v222
	v_mul_f32_e32 v186, v85, v223
	v_mul_f32_e32 v234, v80, v224
	v_mul_f32_e32 v236, v81, v225
	v_mul_f32_e32 v238, v76, v226
	v_mul_f32_e32 v240, v77, v227
	v_mul_f32_e32 v242, v72, v228
	v_mul_f32_e32 v244, v73, v229
	v_mul_f32_e32 v246, v2, v230
	v_mul_f32_e32 v248, v3, v231
	v_cvt_pk_bf16_f32 v216, v179, v180
	v_cvt_pk_bf16_f32 v217, v181, v182
	v_cvt_pk_bf16_f32 v218, v183, v184
	v_cvt_pk_bf16_f32 v219, v185, v186
	v_cvt_pk_bf16_f32 v220, v234, v236
	v_cvt_pk_bf16_f32 v221, v238, v240
	v_cvt_pk_bf16_f32 v222, v242, v244
	v_cvt_pk_bf16_f32 v223, v246, v248
	ds_write_b16 v205, v216 offset:18432
	ds_write_b16_d16_hi v205, v216 offset:18576
	ds_write_b16 v205, v217 offset:18720
	ds_write_b16_d16_hi v205, v217 offset:18864
	ds_write_b16 v205, v218 offset:19008
	ds_write_b16_d16_hi v205, v218 offset:19152
	ds_write_b16 v205, v219 offset:19296
	ds_write_b16_d16_hi v205, v219 offset:19440
	ds_write_b16 v205, v220 offset:19584
	ds_write_b16_d16_hi v205, v220 offset:19728
	ds_write_b16 v205, v221 offset:19872
	ds_write_b16_d16_hi v205, v221 offset:20016
	ds_write_b16 v205, v222 offset:20160
	ds_write_b16_d16_hi v205, v222 offset:20304
	ds_write_b16 v205, v223 offset:20448
	ds_write_b16_d16_hi v205, v223 offset:20592
	s_cbranch_vccz .LBB0_186
	v_bitop3_b32 v1, s2, 64, v151 bitop3:0x36
	v_lshl_add_u32 v1, v1, 2, 0
	v_add_u32_e32 v1, 0x1fb00, v1
	ds_write_b32 v1, v3
	s_branch .LBB0_186
